# epilogue de-serialisation, full pipeline: ConvGLU weight loads of chunks 2-4 fetched one chunk early through four spare quads, only chunk 1 waits on a fresh load (on top of v40)
# baseline (speedup 1.0000x reference)
; __device__ __forceinline__ unsigned pk2(float lo, float hi) { unsigned r; asm("v_cvt_pk_bf16_f32 %0, %1, %2" : "=v"(r) : "v"(lo), "v"(hi)); return r; }
;     __device__ bool next(int i, pg8::Unit& u) const { if (!base.next(i >> 1, u)) return false; u.seg = i & 1; return true; }
;     __device__ __forceinline__ void operator()(const f32x4 (&acc)[2][2][4][2], const pg8::Unit& u, int wr, int wc, int fr, int fq) const {
;     ...
;             for (int n = 0; n < 2; ++n) {
;                 const f32x4 w0 = *(const f32x4*)(cw + j0 + 4 * n), w1 = *(const f32x4*)(cw + DFF + j0 + 4 * n), w2 = *(const f32x4*)(cw + 2 * DFF + j0 + 4 * n), bs = *(const f32x4*)(cb + j0 + 4 * n);
;                 f32x4 o[4];
; #pragma unroll
;                 for (int e = 0; e < 4; ++e) {
;                     float t[4], sx[4];
; #pragma unroll
;                     for (int m = 0; m < 4; ++m) { const float gv = acc[ai][0][m][n][e]; t[m] = __shfl(gv, psrc); sx[m] = __shfl(gv, nsrc); }
; #pragma unroll
;                     for (int m = 0; m < 4; ++m) { const float gv = acc[ai][0][m][n][e];
;                         const float prev = (fr == 0) ? (m > 0 ? t[m > 0 ? m - 1 : 0] : 0.f) : t[m];
;                         const float next = (fr == 15) ? (m < 3 ? sx[m < 3 ? m + 1 : 3] : 0.f) : sx[m];
;                         const float y = w0[e] * prev + w1[e] * gv + w2[e] * next + bs[e];
;                         o[m][e] = gelu_f(y) * acc[ai][1][m][n][e]; } }
; #pragma unroll
;                 for (int m = 0; m < 4; ++m) { const int rho = 16 * m + fr;
;                     if (rho != 0 && rho != 63) { u32x2 wv; wv.x = pk2(o[m][0], o[m][1]); wv.y = pk2(o[m][2], o[m][3]);
;                         *(u32x2*)(act + (size_t)(kb * 64 + rho) * DFF + j0 + 4 * n) = wv; } }
.LBB0_891:
	s_or_b64 exec, exec, s[14:15]
	v_readlane_b32 s76, v246, 25
	v_readlane_b32 s88, v246, 37
	v_readlane_b32 s89, v246, 38
	v_readlane_b32 s90, v246, 39
	v_readlane_b32 s91, v246, 40
	s_mov_b64 s[16:17], s[88:89]
	v_lshlrev_b64 v[128:129], 2, v[168:169]
	s_mov_b64 s[18:19], s[90:91]
	v_lshl_add_u64 v[170:171], s[16:17], 0, v[128:129]
	v_lshl_add_u64 v[176:177], s[40:41], 0, v[128:129]
	v_lshl_add_u64 v[172:173], s[18:19], 0, v[128:129]
	v_lshl_add_u64 v[174:175], s[38:39], 0, v[128:129]
	v_add_u32_e32 v243, 0x5000, v128
	v_add_u32_e32 v244, 0xa000, v128
	global_load_dwordx4 v[140:143], v[170:171], off
	global_load_dwordx4 v[132:135], v[174:175], off
	global_load_dwordx4 v[136:139], v[176:177], off
	global_load_dwordx4 v[128:131], v[172:173], off
	global_load_dwordx4 v[226:229], v[170:171], off offset:16
	global_load_dwordx4 v[230:233], v243, s[16:17] offset:1552
	global_load_dwordx4 v[234:237], v244, s[16:17] offset:3088
	global_load_dwordx4 v[238:241], v[172:173], off offset:16
	ds_bpermute_b32 v180, v190, v120
	ds_bpermute_b32 v218, v191, v120
	ds_bpermute_b32 v211, v190, v116
	ds_bpermute_b32 v212, v191, v116
	ds_bpermute_b32 v215, v190, v112
	ds_bpermute_b32 v213, v191, v112
	ds_bpermute_b32 v217, v190, v100
	ds_bpermute_b32 v216, v191, v100
	ds_bpermute_b32 v181, v190, v121
	ds_bpermute_b32 v219, v191, v121
	ds_bpermute_b32 v209, v190, v117
	ds_bpermute_b32 v214, v191, v117
	ds_bpermute_b32 v206, v190, v113
	ds_bpermute_b32 v210, v191, v113
	ds_bpermute_b32 v207, v190, v101
	ds_bpermute_b32 v208, v191, v101
	ds_bpermute_b32 v178, v190, v122
	ds_bpermute_b32 v220, v191, v122
	ds_bpermute_b32 v199, v190, v118
	ds_bpermute_b32 v200, v191, v118
	ds_bpermute_b32 v203, v190, v114
	ds_bpermute_b32 v201, v191, v114
	ds_bpermute_b32 v205, v190, v102
	ds_bpermute_b32 v204, v191, v102
	ds_bpermute_b32 v179, v190, v123
	ds_bpermute_b32 v221, v191, v123
	ds_bpermute_b32 v197, v190, v119
	ds_bpermute_b32 v202, v191, v119
	ds_bpermute_b32 v194, v190, v115
	ds_bpermute_b32 v198, v191, v115
	ds_bpermute_b32 v195, v190, v103
	ds_bpermute_b32 v196, v191, v103
	s_lshl_b32 s49, s47, 6
	v_or_b32_e32 v193, s49, v145
	v_readlane_b32 s77, v246, 26
	v_readlane_b32 s78, v246, 27
	v_readlane_b32 s79, v246, 28
	v_readlane_b32 s80, v246, 29
	v_readlane_b32 s81, v246, 30
	v_readlane_b32 s82, v246, 31
	v_readlane_b32 s83, v246, 32
	v_readlane_b32 s84, v246, 33
	v_readlane_b32 s85, v246, 34
	v_readlane_b32 s86, v246, 35
	v_readlane_b32 s87, v246, 36
	s_and_saveexec_b64 s[14:15], s[8:9]
	s_cbranch_execz .LBB0_893
	s_waitcnt lgkmcnt(0)
	v_cndmask_b32_e64 v223, v221, v202, s[4:5]
	v_mov_b32_e32 v224, v123
	s_waitcnt vmcnt(0)
	v_mov_b32_e32 v225, v139
	v_mov_b32_e32 v222, v135
	v_cndmask_b32_e64 v221, v220, v200, s[4:5]
	v_mov_b32_e32 v123, v138
	v_mov_b32_e32 v220, v134
	v_pk_mul_f32 v[222:223], v[224:225], v[222:223]
	v_pk_mul_f32 v[122:123], v[122:123], v[220:221]
	v_mov_b32_e32 v221, v222
	v_mov_b32_e32 v220, v122
	v_pk_fma_f32 v[220:221], v[142:143], v[178:179], v[220:221]
	v_mov_b32_e32 v222, v123
	v_pk_add_f32 v[122:123], v[220:221], v[222:223]
	s_nop 0
	v_pk_add_f32 v[122:123], v[130:131], v[122:123]
	s_nop 0
	v_fma_f32 v220, |v123|, s74, 1.0
	v_rcp_f32_e32 v222, v220
	v_pk_mul_f32 v[220:221], v[122:123], v[122:123]
	v_cmp_gt_f32_e32 vcc, 0, v123
	v_mul_f32_e32 v221, 0xbf38aa3b, v221
	v_fmamk_f32 v223, v222, 0x3f07dc22, v192
	v_exp_f32_e32 v221, v221
	v_fmaak_f32 v223, v222, v223, 0x3f35f0e3
	v_fmaak_f32 v223, v222, v223, 0xbe11a98e
	v_fmaak_f32 v223, v222, v223, 0x3e027906
	v_mul_f32_e32 v222, v222, v223
	v_mul_f32_e32 v221, v221, v222
	v_mul_f32_e32 v222, v123, v221
	v_fma_f32 v221, -v123, v221, v123
	v_cndmask_b32_e32 v123, v221, v222, vcc
	v_fma_f32 v221, |v122|, s74, 1.0
	v_rcp_f32_e32 v221, v221
	v_mul_f32_e32 v222, v127, v123
	v_mul_f32_e32 v123, 0xbf38aa3b, v220
	v_exp_f32_e32 v123, v123
	v_fmamk_f32 v127, v221, 0x3f07dc22, v192
	v_fmaak_f32 v127, v221, v127, 0x3f35f0e3
	v_fmaak_f32 v127, v221, v127, 0xbe11a98e
	v_fmaak_f32 v127, v221, v127, 0x3e027906
	v_mul_f32_e32 v127, v221, v127
	v_mul_f32_e32 v123, v123, v127
	v_mul_f32_e32 v127, v122, v123
	v_fma_f32 v123, -v122, v123, v122
	v_cmp_gt_f32_e32 vcc, 0, v122
	s_nop 1
	v_cndmask_b32_e32 v122, v123, v127, vcc
	v_mul_f32_e32 v220, v126, v122
	v_cndmask_b32_e64 v123, v219, v214, s[4:5]
	v_mov_b32_e32 v126, v121
	v_mov_b32_e32 v127, v137
	v_mov_b32_e32 v122, v133
	v_pk_mul_f32 v[122:123], v[126:127], v[122:123]
	v_cndmask_b32_e64 v127, v218, v212, s[4:5]
	v_mov_b32_e32 v121, v136
	v_mov_b32_e32 v126, v132
	v_pk_mul_f32 v[120:121], v[120:121], v[126:127]
	v_mov_b32_e32 v127, v122
	v_mov_b32_e32 v126, v120
	v_pk_fma_f32 v[126:127], v[140:141], v[180:181], v[126:127]
	v_mov_b32_e32 v122, v121
	v_pk_add_f32 v[120:121], v[126:127], v[122:123]
	s_nop 0
	v_pk_add_f32 v[120:121], v[128:129], v[120:121]
	s_nop 0
	v_fma_f32 v122, |v121|, s74, 1.0
	v_rcp_f32_e32 v126, v122
	v_pk_mul_f32 v[122:123], v[120:121], v[120:121]
	v_cmp_gt_f32_e32 vcc, 0, v121
	v_mul_f32_e32 v123, 0xbf38aa3b, v123
	v_fmamk_f32 v127, v126, 0x3f07dc22, v192
	v_exp_f32_e32 v123, v123
	v_fmaak_f32 v127, v126, v127, 0x3f35f0e3
	v_fmaak_f32 v127, v126, v127, 0xbe11a98e
	v_fmaak_f32 v127, v126, v127, 0x3e027906
	v_mul_f32_e32 v126, v126, v127
	v_mul_f32_e32 v123, v123, v126
	v_mul_f32_e32 v126, v121, v123
	v_fma_f32 v123, -v121, v123, v121
	v_cndmask_b32_e32 v121, v123, v126, vcc
	v_fma_f32 v123, |v120|, s74, 1.0
	v_rcp_f32_e32 v123, v123
	v_mul_f32_e32 v121, v125, v121
	v_mul_f32_e32 v122, 0xbf38aa3b, v122
	v_exp_f32_e32 v122, v122
	v_fmamk_f32 v125, v123, 0x3f07dc22, v192
	v_fmaak_f32 v125, v123, v125, 0x3f35f0e3
	v_fmaak_f32 v125, v123, v125, 0xbe11a98e
	v_fmaak_f32 v125, v123, v125, 0x3e027906
	v_mul_f32_e32 v123, v123, v125
	v_mul_f32_e32 v122, v122, v123
	v_mul_f32_e32 v123, v120, v122
	v_fma_f32 v122, -v120, v122, v120
	v_cmp_gt_f32_e32 vcc, 0, v120
	s_nop 1
	v_cndmask_b32_e32 v120, v122, v123, vcc
	v_mov_b64_e32 v[122:123], s[26:27]
	v_mad_i64_i32 v[122:123], s[16:17], v193, s75, v[122:123]
	v_mul_f32_e32 v120, v124, v120
	v_lshl_add_u64 v[122:123], v[168:169], 1, v[122:123]
	v_cvt_pk_bf16_f32 v120, v120, v121
	v_cvt_pk_bf16_f32 v121, v220, v222
	global_store_dwordx2 v[122:123], v[120:121], off

; __device__ __forceinline__ unsigned pk2(float lo, float hi) { unsigned r; asm("v_cvt_pk_bf16_f32 %0, %1, %2" : "=v"(r) : "v"(lo), "v"(hi)); return r; }
;     __device__ bool next(int i, pg8::Unit& u) const { if (!base.next(i >> 1, u)) return false; u.seg = i & 1; return true; }
;     __device__ __forceinline__ void operator()(const f32x4 (&acc)[2][2][4][2], const pg8::Unit& u, int wr, int wc, int fr, int fq) const {
;     ...
;             for (int n = 0; n < 2; ++n) {
;                 const f32x4 w0 = *(const f32x4*)(cw + j0 + 4 * n), w1 = *(const f32x4*)(cw + DFF + j0 + 4 * n), w2 = *(const f32x4*)(cw + 2 * DFF + j0 + 4 * n), bs = *(const f32x4*)(cb + j0 + 4 * n);
;                 f32x4 o[4];
; #pragma unroll
;                 for (int e = 0; e < 4; ++e) {
;                     float t[4], sx[4];
; #pragma unroll
;                     for (int m = 0; m < 4; ++m) { const float gv = acc[ai][0][m][n][e]; t[m] = __shfl(gv, psrc); sx[m] = __shfl(gv, nsrc); }
; #pragma unroll
;                     for (int m = 0; m < 4; ++m) { const float gv = acc[ai][0][m][n][e];
;                         const float prev = (fr == 0) ? (m > 0 ? t[m > 0 ? m - 1 : 0] : 0.f) : t[m];
;                         const float next = (fr == 15) ? (m < 3 ? sx[m < 3 ? m + 1 : 3] : 0.f) : sx[m];
;                         const float y = w0[e] * prev + w1[e] * gv + w2[e] * next + bs[e];
;                         o[m][e] = gelu_f(y) * acc[ai][1][m][n][e]; } }
; #pragma unroll
;                 for (int m = 0; m < 4; ++m) { const int rho = 16 * m + fr;
;                     if (rho != 0 && rho != 63) { u32x2 wv; wv.x = pk2(o[m][0], o[m][1]); wv.y = pk2(o[m][2], o[m][3]);
;                         *(u32x2*)(act + (size_t)(kb * 64 + rho) * DFF + j0 + 4 * n) = wv; } }
.LBB0_895:
	s_or_b64 exec, exec, s[20:21]
	v_add_co_u32_e32 v96, vcc, 0x5000, v170
	v_mov_b32_e32 v108, v226
	v_mov_b32_e32 v109, v227
	v_mov_b32_e32 v110, v228
	v_mov_b32_e32 v111, v229
	s_nop 0
	v_addc_co_u32_e32 v97, vcc, 0, v171, vcc
	v_add_co_u32_e32 v98, vcc, 0xa000, v170
	ds_bpermute_b32 v120, v190, v88
	s_nop 0
	v_addc_co_u32_e32 v99, vcc, 0, v171, vcc
	v_mov_b32_e32 v100, v230
	v_mov_b32_e32 v101, v231
	v_mov_b32_e32 v102, v232
	v_mov_b32_e32 v103, v233
	v_mov_b32_e32 v104, v234
	v_mov_b32_e32 v105, v235
	v_mov_b32_e32 v106, v236
	v_mov_b32_e32 v107, v237
	s_nop 0
	v_mov_b32_e32 v96, v238
	v_mov_b32_e32 v97, v239
	v_mov_b32_e32 v98, v240
	v_mov_b32_e32 v99, v241
	global_load_dwordx4 v[226:229], v[170:171], off
	global_load_dwordx4 v[230:233], v[174:175], off
	global_load_dwordx4 v[234:237], v[176:177], off
	global_load_dwordx4 v[238:241], v[172:173], off
	ds_bpermute_b32 v181, v191, v88
	ds_bpermute_b32 v140, v190, v84
	ds_bpermute_b32 v141, v191, v84
	ds_bpermute_b32 v178, v190, v80
	ds_bpermute_b32 v142, v191, v80
	ds_bpermute_b32 v180, v190, v68
	ds_bpermute_b32 v179, v191, v68
	ds_bpermute_b32 v121, v190, v89
	ds_bpermute_b32 v194, v191, v89
	ds_bpermute_b32 v138, v190, v85
	ds_bpermute_b32 v143, v191, v85
	ds_bpermute_b32 v135, v190, v81
	ds_bpermute_b32 v139, v191, v81
	ds_bpermute_b32 v136, v190, v69
	ds_bpermute_b32 v137, v191, v69
	ds_bpermute_b32 v118, v190, v90
	ds_bpermute_b32 v195, v191, v90
	ds_bpermute_b32 v128, v190, v86
	ds_bpermute_b32 v129, v191, v86
	ds_bpermute_b32 v132, v190, v82
	ds_bpermute_b32 v130, v191, v82
	ds_bpermute_b32 v134, v190, v70
	ds_bpermute_b32 v133, v191, v70
	ds_bpermute_b32 v119, v190, v91
	ds_bpermute_b32 v196, v191, v91
	ds_bpermute_b32 v126, v190, v87
	ds_bpermute_b32 v131, v191, v87
	ds_bpermute_b32 v122, v190, v83
	ds_bpermute_b32 v127, v191, v83
	ds_bpermute_b32 v124, v190, v71
	ds_bpermute_b32 v125, v191, v71
	s_and_saveexec_b64 s[14:15], s[8:9]
	s_cbranch_execz .LBB0_897
	s_waitcnt lgkmcnt(4)
	v_cndmask_b32_e64 v197, v196, v131, s[4:5]
	v_mov_b32_e32 v198, v91
	v_mov_b32_e32 v199, v107
	v_mov_b32_e32 v196, v103
	v_pk_mul_f32 v[196:197], v[198:199], v[196:197]
	v_cndmask_b32_e64 v199, v195, v129, s[4:5]
	v_mov_b32_e32 v91, v106
	v_mov_b32_e32 v198, v102
	v_pk_mul_f32 v[90:91], v[90:91], v[198:199]
	v_mov_b32_e32 v199, v196
	v_mov_b32_e32 v198, v90
	v_pk_fma_f32 v[198:199], v[110:111], v[118:119], v[198:199]
	v_mov_b32_e32 v196, v91
	v_pk_add_f32 v[90:91], v[198:199], v[196:197]
	v_pk_add_f32 v[90:91], v[98:99], v[90:91]
	s_nop 0
	v_fma_f32 v195, |v91|, s74, 1.0
	v_rcp_f32_e32 v195, v195
	v_pk_mul_f32 v[196:197], v[90:91], v[90:91]
	v_cmp_gt_f32_e32 vcc, 0, v91
	v_mul_f32_e32 v197, 0xbf38aa3b, v197
	v_fmamk_f32 v198, v195, 0x3f07dc22, v192
	v_exp_f32_e32 v197, v197
	v_fmaak_f32 v198, v195, v198, 0x3f35f0e3
	v_fmaak_f32 v198, v195, v198, 0xbe11a98e
	v_fmaak_f32 v198, v195, v198, 0x3e027906
	v_mul_f32_e32 v195, v195, v198
	v_mul_f32_e32 v195, v197, v195
	v_mul_f32_e32 v197, v91, v195
	v_fma_f32 v195, -v91, v195, v91
	v_cndmask_b32_e32 v91, v195, v197, vcc
	v_fma_f32 v195, |v90|, s74, 1.0
	v_rcp_f32_e32 v195, v195
	v_mul_f32_e32 v197, v95, v91
	v_mul_f32_e32 v91, 0xbf38aa3b, v196
	v_exp_f32_e32 v91, v91
	v_fmamk_f32 v95, v195, 0x3f07dc22, v192
	v_fmaak_f32 v95, v195, v95, 0x3f35f0e3
	v_fmaak_f32 v95, v195, v95, 0xbe11a98e
	v_fmaak_f32 v95, v195, v95, 0x3e027906
	v_mul_f32_e32 v95, v195, v95
	v_mul_f32_e32 v91, v91, v95
	v_mul_f32_e32 v95, v90, v91
	v_fma_f32 v91, -v90, v91, v90
	v_cmp_gt_f32_e32 vcc, 0, v90
	s_nop 1
	v_cndmask_b32_e32 v90, v91, v95, vcc
	v_mul_f32_e32 v195, v94, v90
	v_cndmask_b32_e64 v91, v194, v143, s[4:5]
	v_mov_b32_e32 v94, v89
	v_mov_b32_e32 v95, v105
	v_mov_b32_e32 v90, v101
	v_pk_mul_f32 v[90:91], v[94:95], v[90:91]
	v_cndmask_b32_e64 v95, v181, v141, s[4:5]
	v_mov_b32_e32 v89, v104
	v_mov_b32_e32 v94, v100
	v_pk_mul_f32 v[88:89], v[88:89], v[94:95]
	v_mov_b32_e32 v95, v90
	v_mov_b32_e32 v94, v88
	v_pk_fma_f32 v[94:95], v[108:109], v[120:121], v[94:95]
	v_mov_b32_e32 v90, v89
	v_pk_add_f32 v[88:89], v[94:95], v[90:91]
	s_nop 0
	v_pk_add_f32 v[88:89], v[96:97], v[88:89]
	s_nop 0
	v_fma_f32 v90, |v89|, s74, 1.0
	v_rcp_f32_e32 v94, v90
	v_pk_mul_f32 v[90:91], v[88:89], v[88:89]
	v_cmp_gt_f32_e32 vcc, 0, v89
	v_mul_f32_e32 v91, 0xbf38aa3b, v91
	v_fmamk_f32 v95, v94, 0x3f07dc22, v192
	v_exp_f32_e32 v91, v91
	v_fmaak_f32 v95, v94, v95, 0x3f35f0e3
	v_fmaak_f32 v95, v94, v95, 0xbe11a98e
	v_fmaak_f32 v95, v94, v95, 0x3e027906
	v_mul_f32_e32 v94, v94, v95
	v_mul_f32_e32 v91, v91, v94
	v_mul_f32_e32 v94, v89, v91
	v_fma_f32 v91, -v89, v91, v89
	v_cndmask_b32_e32 v89, v91, v94, vcc
	v_fma_f32 v91, |v88|, s74, 1.0
	v_rcp_f32_e32 v91, v91
	v_mul_f32_e32 v89, v93, v89
	v_mul_f32_e32 v90, 0xbf38aa3b, v90
	v_exp_f32_e32 v90, v90
	v_fmamk_f32 v93, v91, 0x3f07dc22, v192
	v_fmaak_f32 v93, v91, v93, 0x3f35f0e3
	v_fmaak_f32 v93, v91, v93, 0xbe11a98e
	v_fmaak_f32 v93, v91, v93, 0x3e027906
	v_mul_f32_e32 v91, v91, v93
	v_mul_f32_e32 v90, v90, v91
	v_mul_f32_e32 v91, v88, v90
	v_fma_f32 v90, -v88, v90, v88
	v_cmp_gt_f32_e32 vcc, 0, v88
	s_nop 1
	v_cndmask_b32_e32 v88, v90, v91, vcc
	v_mov_b64_e32 v[90:91], s[26:27]
	v_mad_i64_i32 v[90:91], s[16:17], v193, s75, v[90:91]
	v_mul_f32_e32 v88, v92, v88
	v_lshl_add_u64 v[90:91], v[168:169], 1, v[90:91]
	v_cvt_pk_bf16_f32 v88, v88, v89
	v_cvt_pk_bf16_f32 v89, v195, v197
	global_store_dwordx2 v[90:91], v[88:89], off offset:8
; __device__ __forceinline__ unsigned pk2(float lo, float hi) { unsigned r; asm("v_cvt_pk_bf16_f32 %0, %1, %2" : "=v"(r) : "v"(lo), "v"(hi)); return r; }
;     __device__ bool next(int i, pg8::Unit& u) const { if (!base.next(i >> 1, u)) return false; u.seg = i & 1; return true; }
;     __device__ __forceinline__ void operator()(const f32x4 (&acc)[2][2][4][2], const pg8::Unit& u, int wr, int wc, int fr, int fq) const {
;     ...
;             for (int n = 0; n < 2; ++n) {
;                 const f32x4 w0 = *(const f32x4*)(cw + j0 + 4 * n), w1 = *(const f32x4*)(cw + DFF + j0 + 4 * n), w2 = *(const f32x4*)(cw + 2 * DFF + j0 + 4 * n), bs = *(const f32x4*)(cb + j0 + 4 * n);
;                 f32x4 o[4];
; #pragma unroll
;                 for (int e = 0; e < 4; ++e) {
;                     float t[4], sx[4];
; #pragma unroll
;                     for (int m = 0; m < 4; ++m) { const float gv = acc[ai][0][m][n][e]; t[m] = __shfl(gv, psrc); sx[m] = __shfl(gv, nsrc); }
; #pragma unroll
;                     for (int m = 0; m < 4; ++m) { const float gv = acc[ai][0][m][n][e];
;                         const float prev = (fr == 0) ? (m > 0 ? t[m > 0 ? m - 1 : 0] : 0.f) : t[m];
;                         const float next = (fr == 15) ? (m < 3 ? sx[m < 3 ? m + 1 : 3] : 0.f) : sx[m];
;                         const float y = w0[e] * prev + w1[e] * gv + w2[e] * next + bs[e];
;                         o[m][e] = gelu_f(y) * acc[ai][1][m][n][e]; } }
; #pragma unroll
;                 for (int m = 0; m < 4; ++m) { const int rho = 16 * m + fr;
;                     if (rho != 0 && rho != 63) { u32x2 wv; wv.x = pk2(o[m][0], o[m][1]); wv.y = pk2(o[m][2], o[m][3]);
;                         *(u32x2*)(act + (size_t)(kb * 64 + rho) * DFF + j0 + 4 * n) = wv; } }
.LBB0_897:
	s_or_b64 exec, exec, s[14:15]
	v_mov_b32_e32 v92, v108
	v_mov_b32_e32 v93, v104
	s_waitcnt lgkmcnt(14)
	v_cndmask_b32_e64 v88, v180, v178, s[10:11]
	v_cndmask_b32_e64 v89, v179, 0, s[4:5]
	v_cndmask_b32_e64 v90, v178, v140, s[10:11]
	v_cndmask_b32_e64 v91, v142, v179, s[4:5]
	v_pk_mul_f32 v[88:89], v[92:93], v[88:89]
	v_pk_mul_f32 v[90:91], v[92:93], v[90:91]
	v_mov_b32_e32 v94, v68
	v_mov_b32_e32 v95, v80
	v_mov_b32_e32 v178, v88
	v_mov_b32_e32 v179, v90
	v_pk_fma_f32 v[94:95], v[94:95], v[100:101], v[178:179] op_sel_hi:[1,0,1]
	v_mov_b32_e32 v90, v89
	v_pk_add_f32 v[88:89], v[94:95], v[90:91]
	v_cndmask_b32_e64 v94, v140, v120, s[10:11]
	v_pk_add_f32 v[88:89], v[96:97], v[88:89] op_sel_hi:[0,1]
	v_fma_f32 v68, |v89|, s74, 1.0
	v_rcp_f32_e32 v68, v68
	v_cndmask_b32_e64 v95, v141, v142, s[4:5]
	v_pk_mul_f32 v[90:91], v[88:89], v[88:89]
	v_pk_mul_f32 v[92:93], v[92:93], v[94:95]
	v_cndmask_b32_e64 v94, v138, v121, s[10:11]
	v_cndmask_b32_e64 v95, v143, v139, s[4:5]
	v_mov_b32_e32 v104, v109
	v_fmamk_f32 v80, v68, 0x3f07dc22, v192
	v_mul_f32_e32 v91, 0xbf38aa3b, v91
	v_pk_mul_f32 v[94:95], v[104:105], v[94:95]
	v_fmaak_f32 v80, v68, v80, 0x3f35f0e3
	v_exp_f32_e32 v91, v91
	v_mov_b32_e32 v108, v92
	v_mov_b32_e32 v109, v94
	v_fmaak_f32 v80, v68, v80, 0xbe11a98e
	v_pk_fma_f32 v[84:85], v[84:85], v[100:101], v[108:109]
	v_mov_b32_e32 v94, v93
	v_fmaak_f32 v80, v68, v80, 0x3e027906
	v_pk_add_f32 v[84:85], v[84:85], v[94:95]
	v_mul_f32_e32 v68, v68, v80
	v_pk_add_f32 v[84:85], v[96:97], v[84:85]
	v_mul_f32_e32 v68, v91, v68
	v_fma_f32 v91, |v84|, s74, 1.0
	v_rcp_f32_e32 v91, v91
	v_mul_f32_e32 v80, v89, v68
	v_fma_f32 v68, -v89, v68, v89
	v_cmp_gt_f32_e64 s[14:15], 0, v89
	v_pk_mul_f32 v[92:93], v[84:85], v[84:85]
	v_cndmask_b32_e64 v94, v136, v135, s[10:11]
	v_cndmask_b32_e64 v68, v68, v80, s[14:15]
	v_mul_f32_e32 v89, v72, v68
	v_fmamk_f32 v68, v91, 0x3f07dc22, v192
	v_mul_f32_e32 v72, 0xbf38aa3b, v92
	v_fmaak_f32 v68, v91, v68, 0x3f35f0e3
	v_exp_f32_e32 v72, v72
	v_fmaak_f32 v68, v91, v68, 0xbe11a98e
	v_fmaak_f32 v68, v91, v68, 0x3e027906
	v_fma_f32 v80, |v85|, s74, 1.0
	v_mul_f32_e32 v68, v91, v68
	v_rcp_f32_e32 v80, v80
	v_mul_f32_e32 v68, v72, v68
	v_mul_f32_e32 v72, v84, v68
	v_fma_f32 v68, -v84, v68, v84
	v_cmp_gt_f32_e64 s[14:15], 0, v84
	v_cndmask_b32_e64 v92, v135, v138, s[10:11]
	v_cndmask_b32_e64 v95, v137, 0, s[4:5]
	v_cndmask_b32_e64 v68, v68, v72, s[14:15]
	v_mul_f32_e32 v91, v76, v68
	v_fmamk_f32 v68, v80, 0x3f07dc22, v192
	v_mul_f32_e32 v72, 0xbf38aa3b, v93
	v_fmaak_f32 v68, v80, v68, 0x3f35f0e3
	v_exp_f32_e32 v72, v72
	v_fmaak_f32 v68, v80, v68, 0xbe11a98e
	v_fmaak_f32 v68, v80, v68, 0x3e027906
	v_mul_f32_e32 v68, v80, v68
	v_cndmask_b32_e64 v93, v139, v137, s[4:5]
	v_mul_f32_e32 v68, v72, v68
	v_pk_mul_f32 v[92:93], v[104:105], v[92:93]
	v_pk_mul_f32 v[94:95], v[104:105], v[94:95]
	v_mul_f32_e32 v72, v85, v68
	v_fma_f32 v76, -v85, v68, v85
	v_mov_b32_e32 v80, v69
	v_mov_b32_e32 v68, v94
	v_mov_b32_e32 v69, v92
	v_pk_fma_f32 v[68:69], v[80:81], v[100:101], v[68:69] op_sel:[0,1,0]
	v_mov_b32_e32 v92, v95
	v_pk_add_f32 v[68:69], v[68:69], v[92:93]
	v_cmp_gt_f32_e64 s[14:15], 0, v85
	v_pk_add_f32 v[68:69], v[96:97], v[68:69] op_sel:[1,0]
	v_mov_b32_e32 v84, v110
	v_fma_f32 v80, |v69|, s74, 1.0
	v_rcp_f32_e32 v80, v80
	v_cndmask_b32_e64 v72, v76, v72, s[14:15]
	v_mul_f32_e32 v100, v77, v72
	v_mov_b32_e32 v85, v106
	v_fmamk_f32 v72, v80, 0x3f07dc22, v192
	v_fmaak_f32 v72, v80, v72, 0x3f35f0e3
	v_fmaak_f32 v72, v80, v72, 0xbe11a98e
	v_fmaak_f32 v72, v80, v72, 0x3e027906
	v_mul_f32_e32 v72, v80, v72
	s_waitcnt lgkmcnt(9)
	v_cndmask_b32_e64 v80, v134, v132, s[10:11]
	s_waitcnt lgkmcnt(8)
	v_cndmask_b32_e64 v81, v133, 0, s[4:5]
	v_cndmask_b32_e64 v92, v132, v128, s[10:11]
	v_cndmask_b32_e64 v93, v130, v133, s[4:5]
	v_pk_mul_f32 v[80:81], v[84:85], v[80:81]
	v_pk_mul_f32 v[92:93], v[84:85], v[92:93]
	v_pk_mul_f32 v[76:77], v[68:69], v[68:69]
	v_mov_b32_e32 v94, v70
	v_mov_b32_e32 v95, v82
	v_mov_b32_e32 v96, v80
	v_mov_b32_e32 v97, v92
	v_mul_f32_e32 v77, 0xbf38aa3b, v77
	v_pk_fma_f32 v[94:95], v[94:95], v[102:103], v[96:97] op_sel_hi:[1,0,1]
	v_mov_b32_e32 v92, v81
	v_exp_f32_e32 v77, v77
	v_pk_add_f32 v[80:81], v[94:95], v[92:93]
	v_cndmask_b32_e64 v92, v128, v118, s[10:11]
	v_pk_add_f32 v[80:81], v[98:99], v[80:81] op_sel_hi:[0,1]
	v_fma_f32 v70, |v81|, s74, 1.0
	v_rcp_f32_e32 v70, v70
	v_mul_f32_e32 v72, v77, v72
	v_cndmask_b32_e64 v93, v129, v130, s[4:5]
	v_mul_f32_e32 v77, v69, v72
	v_fma_f32 v72, -v69, v72, v69
	v_cmp_gt_f32_e64 s[16:17], 0, v69
	v_pk_mul_f32 v[84:85], v[84:85], v[92:93]
	s_waitcnt lgkmcnt(5)
	v_cndmask_b32_e64 v92, v126, v119, s[10:11]
	s_waitcnt lgkmcnt(2)
	v_cndmask_b32_e64 v93, v131, v127, s[4:5]
	v_mov_b32_e32 v106, v111
	v_cndmask_b32_e64 v69, v72, v77, s[16:17]
	v_pk_mul_f32 v[92:93], v[106:107], v[92:93]
	v_mul_f32_e32 v69, v73, v69
	v_pk_mul_f32 v[72:73], v[80:81], v[80:81]
	v_fmamk_f32 v77, v70, 0x3f07dc22, v192
	v_mov_b32_e32 v94, v84
	v_mov_b32_e32 v95, v92
	v_fmaak_f32 v77, v70, v77, 0x3f35f0e3
	v_mul_f32_e32 v73, 0xbf38aa3b, v73
	v_pk_fma_f32 v[86:87], v[86:87], v[102:103], v[94:95]
	v_mov_b32_e32 v92, v85
	v_exp_f32_e32 v73, v73
	v_fmaak_f32 v77, v70, v77, 0xbe11a98e
	v_pk_add_f32 v[84:85], v[86:87], v[92:93]
	v_fmaak_f32 v77, v70, v77, 0x3e027906
	v_pk_add_f32 v[84:85], v[98:99], v[84:85]
	v_mul_f32_e32 v70, v70, v77
	v_fma_f32 v77, |v84|, s74, 1.0
	v_rcp_f32_e32 v77, v77
	v_mul_f32_e32 v70, v73, v70
	v_mul_f32_e32 v73, v81, v70
	v_fma_f32 v70, -v81, v70, v81
	v_cmp_gt_f32_e64 s[18:19], 0, v81
	v_pk_mul_f32 v[86:87], v[84:85], v[84:85]
	s_waitcnt lgkmcnt(1)
; __device__ __forceinline__ unsigned pk2(float lo, float hi) { unsigned r; asm("v_cvt_pk_bf16_f32 %0, %1, %2" : "=v"(r) : "v"(lo), "v"(hi)); return r; }
;     __device__ bool next(int i, pg8::Unit& u) const { if (!base.next(i >> 1, u)) return false; u.seg = i & 1; return true; }
;     __device__ __forceinline__ void operator()(const f32x4 (&acc)[2][2][4][2], const pg8::Unit& u, int wr, int wc, int fr, int fq) const {
;     ...
;                     for (int m = 0; m < 4; ++m) { const float gv = acc[ai][0][m][n][e];
;                         const float prev = (fr == 0) ? (m > 0 ? t[m > 0 ? m - 1 : 0] : 0.f) : t[m];
;                         const float next = (fr == 15) ? (m < 3 ? sx[m < 3 ? m + 1 : 3] : 0.f) : sx[m];
;                         const float y = w0[e] * prev + w1[e] * gv + w2[e] * next + bs[e];
;                         o[m][e] = gelu_f(y) * acc[ai][1][m][n][e]; } }
; #pragma unroll
;                 for (int m = 0; m < 4; ++m) { const int rho = 16 * m + fr;
;                     if (rho != 0 && rho != 63) { u32x2 wv; wv.x = pk2(o[m][0], o[m][1]); wv.y = pk2(o[m][2], o[m][3]);
;                         *(u32x2*)(act + (size_t)(kb * 64 + rho) * DFF + j0 + 4 * n) = wv; } }
	v_cndmask_b32_e64 v92, v124, v122, s[10:11]
	v_cndmask_b32_e64 v70, v70, v73, s[18:19]
	v_mul_f32_e32 v73, v74, v70
	v_fmamk_f32 v70, v77, 0x3f07dc22, v192
	v_fmaak_f32 v70, v77, v70, 0x3f35f0e3
	v_mul_f32_e32 v74, 0xbf38aa3b, v86
	v_exp_f32_e32 v74, v74
	v_fmaak_f32 v70, v77, v70, 0xbe11a98e
	v_fmaak_f32 v70, v77, v70, 0x3e027906
	v_mul_f32_e32 v70, v77, v70
	v_fma_f32 v77, |v85|, s74, 1.0
	v_rcp_f32_e32 v77, v77
	v_mul_f32_e32 v70, v74, v70
	v_mul_f32_e32 v74, v84, v70
	v_fma_f32 v70, -v84, v70, v84
	v_cmp_gt_f32_e64 s[18:19], 0, v84
	v_cndmask_b32_e64 v86, v122, v126, s[10:11]
	s_waitcnt lgkmcnt(0)
	v_cndmask_b32_e64 v93, v125, 0, s[4:5]
	v_cndmask_b32_e64 v70, v70, v74, s[18:19]
	v_mul_f32_e32 v81, v78, v70
	v_fmamk_f32 v70, v77, 0x3f07dc22, v192
	v_mul_f32_e32 v74, 0xbf38aa3b, v87
	v_fmaak_f32 v70, v77, v70, 0x3f35f0e3
	v_exp_f32_e32 v74, v74
	v_fmaak_f32 v70, v77, v70, 0xbe11a98e
	v_fmaak_f32 v70, v77, v70, 0x3e027906
	v_mul_f32_e32 v70, v77, v70
	v_cndmask_b32_e64 v87, v127, v125, s[4:5]
	v_mul_f32_e32 v70, v74, v70
	v_pk_mul_f32 v[86:87], v[106:107], v[86:87]
	v_pk_mul_f32 v[92:93], v[106:107], v[92:93]
	v_mul_f32_e32 v77, v85, v70
	v_fma_f32 v78, -v85, v70, v85
	v_mov_b32_e32 v82, v71
	v_mov_b32_e32 v70, v103
	v_mov_b32_e32 v94, v92
	v_mov_b32_e32 v95, v86
	v_pk_fma_f32 v[70:71], v[82:83], v[70:71], v[94:95] op_sel_hi:[1,0,1]
	v_mov_b32_e32 v86, v93
	v_pk_add_f32 v[70:71], v[70:71], v[86:87]
	v_mov_b32_e32 v74, v99
	v_pk_add_f32 v[70:71], v[74:75], v[70:71] op_sel_hi:[0,1]
	v_fma_f32 v74, |v71|, s74, 1.0
	v_rcp_f32_e32 v74, v74
	v_cmp_gt_f32_e64 s[18:19], 0, v85
	v_cmp_gt_f32_e64 s[20:21], 0, v71
	v_cmp_gt_f32_e32 vcc, 0, v88
	v_cndmask_b32_e64 v77, v78, v77, s[18:19]
	v_fmamk_f32 v78, v74, 0x3f07dc22, v192
	v_mul_f32_e32 v77, v79, v77
	v_fmaak_f32 v82, v74, v78, 0x3f35f0e3
	v_pk_mul_f32 v[78:79], v[70:71], v[70:71]
	v_fmaak_f32 v82, v74, v82, 0xbe11a98e
	v_mul_f32_e32 v79, 0xbf38aa3b, v79
	v_exp_f32_e32 v79, v79
	v_fmaak_f32 v82, v74, v82, 0x3e027906
	v_mul_f32_e32 v74, v74, v82
	v_cmp_gt_f32_e64 s[14:15], 0, v68
	v_mul_f32_e32 v74, v79, v74
	v_mul_f32_e32 v79, v71, v74
	v_fma_f32 v74, -v71, v74, v71
	v_cndmask_b32_e64 v71, v74, v79, s[20:21]
	v_cmp_gt_f32_e64 s[16:17], 0, v80
	v_cmp_gt_f32_e64 s[18:19], 0, v70
	v_mul_f32_e32 v71, v75, v71
	v_cvt_pk_bf16_f32 v74, v91, v100
	v_cvt_pk_bf16_f32 v75, v81, v77
	global_store_dwordx2 v[114:115], v[74:75], off offset:8
	v_cvt_pk_bf16_f32 v74, v89, v69
	v_cvt_pk_bf16_f32 v75, v73, v71
	global_store_dwordx2 v[116:117], v[74:75], off offset:8
	s_and_saveexec_b64 s[20:21], s[6:7]
	s_cbranch_execz .LBB0_899
	v_fma_f32 v69, |v88|, s74, 1.0
	v_rcp_f32_e32 v69, v69
	v_mul_f32_e32 v71, 0xbf38aa3b, v90
	v_exp_f32_e32 v71, v71
	v_fma_f32 v73, |v68|, s74, 1.0
	v_fmamk_f32 v74, v69, 0x3f07dc22, v192
	v_fmaak_f32 v74, v69, v74, 0x3f35f0e3
	v_fmaak_f32 v74, v69, v74, 0xbe11a98e
	v_fmaak_f32 v74, v69, v74, 0x3e027906
	v_mul_f32_e32 v69, v69, v74
	v_rcp_f32_e32 v73, v73
	v_mul_f32_e32 v69, v71, v69
	v_mul_f32_e32 v71, v88, v69
	v_fma_f32 v69, -v88, v69, v88
	v_cndmask_b32_e32 v69, v69, v71, vcc
	v_mul_f32_e32 v64, v64, v69
	v_fmamk_f32 v69, v73, 0x3f07dc22, v192
	v_fmaak_f32 v69, v73, v69, 0x3f35f0e3
	v_mul_f32_e32 v71, 0xbf38aa3b, v76
	v_exp_f32_e32 v71, v71
	v_fmaak_f32 v69, v73, v69, 0xbe11a98e
	v_fmaak_f32 v69, v73, v69, 0x3e027906
	v_mul_f32_e32 v69, v73, v69
	v_fma_f32 v73, |v80|, s74, 1.0
	v_rcp_f32_e32 v73, v73
	v_mul_f32_e32 v69, v71, v69
	v_mul_f32_e32 v71, v68, v69
	v_fma_f32 v68, -v68, v69, v68
	v_cndmask_b32_e64 v68, v68, v71, s[14:15]
	v_mul_f32_e32 v65, v65, v68
	v_fmamk_f32 v68, v73, 0x3f07dc22, v192
	v_mul_f32_e32 v69, 0xbf38aa3b, v72
	v_fmaak_f32 v68, v73, v68, 0x3f35f0e3
	v_exp_f32_e32 v69, v69
	v_fmaak_f32 v68, v73, v68, 0xbe11a98e
	v_fmaak_f32 v68, v73, v68, 0x3e027906
	v_fma_f32 v71, |v70|, s74, 1.0
	v_mul_f32_e32 v68, v73, v68
	v_rcp_f32_e32 v71, v71
	v_mul_f32_e32 v68, v69, v68
	v_mul_f32_e32 v69, v80, v68
	v_fma_f32 v68, -v80, v68, v80
	v_cndmask_b32_e64 v68, v68, v69, s[16:17]
	v_mul_f32_e32 v66, v66, v68
	v_fmamk_f32 v68, v71, 0x3f07dc22, v192
	v_mul_f32_e32 v69, 0xbf38aa3b, v78
	v_fmaak_f32 v68, v71, v68, 0x3f35f0e3
	v_exp_f32_e32 v69, v69
	v_fmaak_f32 v68, v71, v68, 0xbe11a98e
	v_fmaak_f32 v68, v71, v68, 0x3e027906
	v_mul_f32_e32 v68, v71, v68
	v_mul_f32_e32 v68, v69, v68
	v_mul_f32_e32 v69, v70, v68
	v_fma_f32 v68, -v70, v68, v70
	v_cndmask_b32_e64 v68, v68, v69, s[18:19]
	v_mul_f32_e32 v67, v67, v68
	v_cvt_pk_bf16_f32 v64, v64, v65
	v_cvt_pk_bf16_f32 v65, v66, v67
	v_mov_b64_e32 v[66:67], s[26:27]
	v_mad_i64_i32 v[66:67], s[14:15], v123, s75, v[66:67]
	v_lshl_add_u64 v[66:67], v[168:169], 1, v[66:67]
	global_store_dwordx2 v[66:67], v[64:65], off offset:8

; __device__ __forceinline__ unsigned pk2(float lo, float hi) { unsigned r; asm("v_cvt_pk_bf16_f32 %0, %1, %2" : "=v"(r) : "v"(lo), "v"(hi)); return r; }
;     __device__ bool next(int i, pg8::Unit& u) const { if (!base.next(i >> 1, u)) return false; u.seg = i & 1; return true; }
;     __device__ __forceinline__ void operator()(const f32x4 (&acc)[2][2][4][2], const pg8::Unit& u, int wr, int wc, int fr, int fq) const {
;     ...
;             for (int n = 0; n < 2; ++n) {
;                 const f32x4 w0 = *(const f32x4*)(cw + j0 + 4 * n), w1 = *(const f32x4*)(cw + DFF + j0 + 4 * n), w2 = *(const f32x4*)(cw + 2 * DFF + j0 + 4 * n), bs = *(const f32x4*)(cb + j0 + 4 * n);
;                 f32x4 o[4];
; #pragma unroll
;                 for (int e = 0; e < 4; ++e) {
;                     float t[4], sx[4];
; #pragma unroll
;                     for (int m = 0; m < 4; ++m) { const float gv = acc[ai][0][m][n][e]; t[m] = __shfl(gv, psrc); sx[m] = __shfl(gv, nsrc); }
; #pragma unroll
;                     for (int m = 0; m < 4; ++m) { const float gv = acc[ai][0][m][n][e];
;                         const float prev = (fr == 0) ? (m > 0 ? t[m > 0 ? m - 1 : 0] : 0.f) : t[m];
;                         const float next = (fr == 15) ? (m < 3 ? sx[m < 3 ? m + 1 : 3] : 0.f) : sx[m];
;                         const float y = w0[e] * prev + w1[e] * gv + w2[e] * next + bs[e];
;                         o[m][e] = gelu_f(y) * acc[ai][1][m][n][e]; } }
; #pragma unroll
;                 for (int m = 0; m < 4; ++m) { const int rho = 16 * m + fr;
;                     if (rho != 0 && rho != 63) { u32x2 wv; wv.x = pk2(o[m][0], o[m][1]); wv.y = pk2(o[m][2], o[m][3]);
;                         *(u32x2*)(act + (size_t)(kb * 64 + rho) * DFF + j0 + 4 * n) = wv; } }
.LBB0_905:
	s_or_b64 exec, exec, s[14:15]
	s_waitcnt vmcnt(2)
	v_mov_b32_e32 v76, v226
	v_mov_b32_e32 v77, v227
	v_mov_b32_e32 v78, v228
	v_mov_b32_e32 v79, v229
	v_mov_b32_e32 v68, v230
	v_mov_b32_e32 v69, v231
	v_mov_b32_e32 v70, v232
	v_mov_b32_e32 v71, v233
	v_mov_b32_e32 v72, v234
	v_mov_b32_e32 v73, v235
	v_mov_b32_e32 v74, v236
	v_mov_b32_e32 v75, v237
	v_mov_b32_e32 v64, v238
	v_mov_b32_e32 v65, v239
	v_mov_b32_e32 v66, v240
	v_mov_b32_e32 v67, v241
	global_load_dwordx4 v[226:229], v[170:171], off offset:16
	global_load_dwordx4 v[230:233], v[80:81], off
	global_load_dwordx4 v[234:237], v[82:83], off
	global_load_dwordx4 v[238:241], v[172:173], off offset:16
	ds_bpermute_b32 v86, v190, v60
	ds_bpermute_b32 v115, v191, v60
	ds_bpermute_b32 v106, v190, v52
	ds_bpermute_b32 v107, v191, v52
	ds_bpermute_b32 v110, v190, v48
	ds_bpermute_b32 v108, v191, v48
	ds_bpermute_b32 v114, v190, v44
	ds_bpermute_b32 v111, v191, v44
	ds_bpermute_b32 v87, v190, v61
	ds_bpermute_b32 v116, v191, v61
	ds_bpermute_b32 v104, v190, v53
	ds_bpermute_b32 v109, v191, v53
	ds_bpermute_b32 v101, v190, v49
	ds_bpermute_b32 v105, v191, v49
	ds_bpermute_b32 v102, v190, v45
	ds_bpermute_b32 v103, v191, v45
	ds_bpermute_b32 v84, v190, v62
	ds_bpermute_b32 v117, v191, v62
	ds_bpermute_b32 v94, v190, v54
	ds_bpermute_b32 v95, v191, v54
	ds_bpermute_b32 v98, v190, v50
	ds_bpermute_b32 v96, v191, v50
	ds_bpermute_b32 v100, v190, v46
	ds_bpermute_b32 v99, v191, v46
	ds_bpermute_b32 v85, v190, v63
	ds_bpermute_b32 v118, v191, v63
	ds_bpermute_b32 v92, v190, v55
	ds_bpermute_b32 v97, v191, v55
	ds_bpermute_b32 v89, v190, v51
	ds_bpermute_b32 v93, v191, v51
	ds_bpermute_b32 v90, v190, v47
	ds_bpermute_b32 v91, v191, v47
	s_lshl_b32 s47, s18, 6
	v_or_b32_e32 v88, s47, v145
	s_and_saveexec_b64 s[14:15], s[8:9]
	s_cbranch_execz .LBB0_907
	s_waitcnt lgkmcnt(4)
	v_cndmask_b32_e64 v119, v118, v97, s[4:5]
	v_mov_b32_e32 v120, v63
	v_mov_b32_e32 v121, v75
	v_mov_b32_e32 v118, v71
	v_pk_mul_f32 v[118:119], v[120:121], v[118:119]
	v_cndmask_b32_e64 v121, v117, v95, s[4:5]
	v_mov_b32_e32 v63, v74
	v_mov_b32_e32 v120, v70
	v_pk_mul_f32 v[62:63], v[62:63], v[120:121]
	v_mov_b32_e32 v121, v118
	v_mov_b32_e32 v120, v62
	v_pk_fma_f32 v[120:121], v[78:79], v[84:85], v[120:121]
	v_mov_b32_e32 v118, v63
	v_pk_add_f32 v[62:63], v[120:121], v[118:119]
	v_pk_add_f32 v[62:63], v[66:67], v[62:63]
	s_nop 0
	v_fma_f32 v117, |v63|, s74, 1.0
	v_rcp_f32_e32 v117, v117
	v_pk_mul_f32 v[118:119], v[62:63], v[62:63]
	v_cmp_gt_f32_e32 vcc, 0, v63
	v_mul_f32_e32 v119, 0xbf38aa3b, v119
	v_fmamk_f32 v120, v117, 0x3f07dc22, v192
	v_exp_f32_e32 v119, v119
	v_fmaak_f32 v120, v117, v120, 0x3f35f0e3
	v_fmaak_f32 v120, v117, v120, 0xbe11a98e
	v_fmaak_f32 v120, v117, v120, 0x3e027906
	v_mul_f32_e32 v117, v117, v120
	v_mul_f32_e32 v117, v119, v117
	v_mul_f32_e32 v119, v63, v117
	v_fma_f32 v117, -v63, v117, v63
	v_cndmask_b32_e32 v63, v117, v119, vcc
	v_fma_f32 v117, |v62|, s74, 1.0
	v_rcp_f32_e32 v117, v117
	v_mul_f32_e32 v119, v59, v63
	v_mul_f32_e32 v59, 0xbf38aa3b, v118
	v_exp_f32_e32 v59, v59
	v_fmamk_f32 v63, v117, 0x3f07dc22, v192
	v_fmaak_f32 v63, v117, v63, 0x3f35f0e3
	v_fmaak_f32 v63, v117, v63, 0xbe11a98e
	v_fmaak_f32 v63, v117, v63, 0x3e027906
	v_mul_f32_e32 v63, v117, v63
	v_mul_f32_e32 v59, v59, v63
	v_mul_f32_e32 v63, v62, v59
	v_fma_f32 v59, -v62, v59, v62
	v_cmp_gt_f32_e32 vcc, 0, v62
	v_mov_b32_e32 v62, v61
	v_mov_b32_e32 v61, v72
	v_cndmask_b32_e32 v59, v59, v63, vcc
	v_mul_f32_e32 v117, v58, v59
	v_cndmask_b32_e64 v59, v116, v109, s[4:5]
	v_mov_b32_e32 v63, v73
	v_mov_b32_e32 v58, v69
	v_pk_mul_f32 v[58:59], v[62:63], v[58:59]
	v_cndmask_b32_e64 v63, v115, v107, s[4:5]
	v_mov_b32_e32 v62, v68
	v_pk_mul_f32 v[60:61], v[60:61], v[62:63]
	v_mov_b32_e32 v63, v58
	v_mov_b32_e32 v62, v60
	v_pk_fma_f32 v[62:63], v[76:77], v[86:87], v[62:63]
	v_mov_b32_e32 v58, v61
	v_pk_add_f32 v[58:59], v[62:63], v[58:59]
	s_nop 0
	v_pk_add_f32 v[58:59], v[64:65], v[58:59]
	s_nop 0
	v_fma_f32 v60, |v59|, s74, 1.0
	v_rcp_f32_e32 v62, v60
	v_pk_mul_f32 v[60:61], v[58:59], v[58:59]
	v_cmp_gt_f32_e32 vcc, 0, v59
	v_mul_f32_e32 v61, 0xbf38aa3b, v61
	v_fmamk_f32 v63, v62, 0x3f07dc22, v192
	v_exp_f32_e32 v61, v61
	v_fmaak_f32 v63, v62, v63, 0x3f35f0e3
	v_fmaak_f32 v63, v62, v63, 0xbe11a98e
	v_fmaak_f32 v63, v62, v63, 0x3e027906
	v_mul_f32_e32 v62, v62, v63
	v_mul_f32_e32 v61, v61, v62
	v_mul_f32_e32 v62, v59, v61
	v_fma_f32 v61, -v59, v61, v59
	v_cndmask_b32_e32 v59, v61, v62, vcc
	v_fma_f32 v61, |v58|, s74, 1.0
	v_rcp_f32_e32 v61, v61
	v_mul_f32_e32 v57, v57, v59
	v_mul_f32_e32 v59, 0xbf38aa3b, v60
	v_exp_f32_e32 v59, v59
	v_fmamk_f32 v60, v61, 0x3f07dc22, v192
	v_fmaak_f32 v60, v61, v60, 0x3f35f0e3
	v_fmaak_f32 v60, v61, v60, 0xbe11a98e
	v_fmaak_f32 v60, v61, v60, 0x3e027906
	v_mul_f32_e32 v60, v61, v60
	v_mul_f32_e32 v59, v59, v60
	v_mul_f32_e32 v60, v58, v59
	v_fma_f32 v59, -v58, v59, v58
	v_cmp_gt_f32_e32 vcc, 0, v58
	s_nop 1
	v_cndmask_b32_e32 v58, v59, v60, vcc
	v_mul_f32_e32 v56, v56, v58
	v_mov_b64_e32 v[58:59], s[26:27]
	v_mad_i64_i32 v[58:59], s[16:17], v88, s75, v[58:59]
	v_lshl_add_u64 v[58:59], v[168:169], 1, v[58:59]
	v_cvt_pk_bf16_f32 v56, v56, v57
	v_cvt_pk_bf16_f32 v57, v117, v119
	global_store_dwordx2 v[58:59], v[56:57], off
